# n3 static priority raise moved to waves 0-3 (mirror of the waves 4-7 variant) to pick the faster half
# speedup vs baseline: 1.0022x; 1.0022x over previous
.LBB0_47:
	s_nop 0
	v_readlane_b32 s2, v255, 3
	s_cmp_lt_i32 s2, 6
	s_mov_b64 s[2:3], 0
	v_writelane_b32 v255, s2, 4
	s_mov_b64 s[0:1], -1
	s_mov_b64 s[4:5], 0
	v_writelane_b32 v255, s3, 5
	s_cbranch_scc1 .LBB0_143
	v_readlane_b32 s0, v255, 3
	v_writelane_b32 v255, s18, 6
	s_cmp_gt_i32 s0, 9
	s_nop 0
	v_writelane_b32 v255, s19, 7
	s_cbranch_scc0 .LBB0_140
	s_cmp_gt_i32 s0, 10
	s_cbranch_scc0 .LBB0_287
	v_writelane_b32 v255, s74, 8
	s_cmp_gt_i32 s0, 11
	s_nop 0
	v_writelane_b32 v255, s75, 9
	s_cbranch_scc0 .LBB0_290
	s_cmp_eq_u32 s0, 12
	s_mov_b64 s[0:1], -1
	v_writelane_b32 v255, s0, 4
	s_nop 1
	v_writelane_b32 v255, s1, 5
	s_cbranch_scc0 .LBB0_386
	v_mov_b32_e32 v0, v1
	s_cmpk_gt_i32 s61, 0x1ff
	v_mbcnt_lo_u32_b32 v0, -1, v0
	v_mbcnt_hi_u32_b32 v2, -1, v0
	v_add_u32_e32 v0, s67, v2
	v_ashrrev_i32_e32 v0, 6, v0
	s_movk_i32 s57, 0x800
	v_readfirstlane_b32 s8, v0
	s_mov_b32 s60, 0xf149f2ca
	s_cbranch_scc1 .LBB0_385
	s_cmp_ge_u32 s67, 0x100
	s_cbranch_scc1 .Lmy_n3_prio_skip
	s_setprio 1
